# s_setprio 2 around the post-barrier LDS-DMA issue step of the gate/up and down/out k-loops
# speedup vs baseline: 1.1258x; 1.0057x over previous
.Lgu2_loop:
	s_waitcnt lgkmcnt(8)
	v_mfma_f32_16x16x32_bf16 v[0:3], v[182:185], v[206:209], v[0:3]
	s_add_u32 m0, s101, 0xb000
	ds_read_b128 v[222:225], v153 offset:0
	global_load_lds_dwordx4 v[106:107], off
	v_lshl_add_u64 v[106:107], v[106:107], 0, s[2:3]
	s_waitcnt lgkmcnt(8)
	v_mfma_f32_16x16x32_bf16 v[4:7], v[182:185], v[210:213], v[4:7]
	s_add_u32 m0, s101, 0x10000
	ds_read_b128 v[140:143], v155 offset:16384
	global_load_lds_dwordx4 v[108:109], off
	v_lshl_add_u64 v[108:109], v[108:109], 0, s[2:3]
	s_waitcnt lgkmcnt(8)
	v_mfma_f32_16x16x32_bf16 v[8:11], v[182:185], v[214:217], v[8:11]
	s_add_u32 m0, s101, 0x11000
	ds_read_b128 v[144:147], v155 offset:18432
	global_load_lds_dwordx4 v[110:111], off
	v_lshl_add_u64 v[110:111], v[110:111], 0, s[2:3]
	s_waitcnt lgkmcnt(8)
	v_mfma_f32_16x16x32_bf16 v[12:15], v[182:185], v[218:221], v[12:15]
	s_add_u32 m0, s101, 0x12000
	ds_read_b128 v[116:119], v155 offset:20480
	global_load_lds_dwordx4 v[112:113], off
	v_lshl_add_u64 v[112:113], v[112:113], 0, s[2:3]
	s_waitcnt lgkmcnt(8)
	v_mfma_f32_16x16x32_bf16 v[16:19], v[186:189], v[206:209], v[16:19]
	s_add_u32 m0, s101, 0x13000
	ds_read_b128 v[120:123], v155 offset:22528
	global_load_lds_dwordx4 v[114:115], off
	v_lshl_add_u64 v[114:115], v[114:115], 0, s[2:3]
	v_mfma_f32_16x16x32_bf16 v[20:23], v[186:189], v[210:213], v[20:23]
	ds_read_b128 v[226:229], v153 offset:2048
	v_mfma_f32_16x16x32_bf16 v[24:27], v[186:189], v[214:217], v[24:27]
	ds_read_b128 v[230:233], v153 offset:4096
	v_mfma_f32_16x16x32_bf16 v[28:31], v[186:189], v[218:221], v[28:31]
	ds_read_b128 v[234:237], v153 offset:6144
	s_waitcnt lgkmcnt(11)
	v_mfma_f32_16x16x32_bf16 v[32:35], v[190:193], v[206:209], v[32:35]
	ds_read_b128 v[132:135], v153 offset:8192
	v_mfma_f32_16x16x32_bf16 v[36:39], v[190:193], v[210:213], v[36:39]
	ds_read_b128 v[136:139], v153 offset:10240
	v_mfma_f32_16x16x32_bf16 v[40:43], v[190:193], v[214:217], v[40:43]
	v_mfma_f32_16x16x32_bf16 v[44:47], v[190:193], v[218:221], v[44:47]
	s_waitcnt lgkmcnt(12)
	v_mfma_f32_16x16x32_bf16 v[48:51], v[194:197], v[206:209], v[48:51]
	v_mfma_f32_16x16x32_bf16 v[52:55], v[194:197], v[210:213], v[52:55]
	v_mfma_f32_16x16x32_bf16 v[56:59], v[194:197], v[214:217], v[56:59]
	v_mfma_f32_16x16x32_bf16 v[60:63], v[194:197], v[218:221], v[60:63]
	s_waitcnt lgkmcnt(11)
	v_mfma_f32_16x16x32_bf16 v[64:67], v[198:201], v[206:209], v[64:67]
	v_mfma_f32_16x16x32_bf16 v[68:71], v[198:201], v[210:213], v[68:71]
	v_mfma_f32_16x16x32_bf16 v[72:75], v[198:201], v[214:217], v[72:75]
	v_mfma_f32_16x16x32_bf16 v[76:79], v[198:201], v[218:221], v[76:79]
	s_waitcnt lgkmcnt(10)
	v_mfma_f32_16x16x32_bf16 v[80:83], v[202:205], v[206:209], v[80:83]
	v_mfma_f32_16x16x32_bf16 v[84:87], v[202:205], v[210:213], v[84:87]
	v_mfma_f32_16x16x32_bf16 v[88:91], v[202:205], v[214:217], v[88:91]
	v_mfma_f32_16x16x32_bf16 v[92:95], v[202:205], v[218:221], v[92:95]
	s_waitcnt vmcnt(0) lgkmcnt(0)
	s_barrier
	s_setprio 2
	v_mfma_f32_16x16x32_bf16 v[0:3], v[222:225], v[140:143], v[0:3]
	s_add_u32 m0, s101, 0x0
	ds_read_b128 v[182:185], v150 offset:24576
	global_load_lds_dwordx4 v[96:97], off
	v_lshl_add_u64 v[96:97], v[96:97], 0, s[2:3]
	v_mfma_f32_16x16x32_bf16 v[4:7], v[222:225], v[144:147], v[4:7]
	s_add_u32 m0, s101, 0x1000
	ds_read_b128 v[206:209], v154 offset:32768
	global_load_lds_dwordx4 v[98:99], off
	v_lshl_add_u64 v[98:99], v[98:99], 0, s[2:3]
	v_mfma_f32_16x16x32_bf16 v[8:11], v[222:225], v[116:119], v[8:11]
	s_add_u32 m0, s101, 0x2000
	ds_read_b128 v[210:213], v154 offset:34816
	global_load_lds_dwordx4 v[100:101], off
	v_lshl_add_u64 v[100:101], v[100:101], 0, s[2:3]
	v_mfma_f32_16x16x32_bf16 v[12:15], v[222:225], v[120:123], v[12:15]
	s_add_u32 m0, s101, 0x3000
	ds_read_b128 v[214:217], v154 offset:36864
	global_load_lds_dwordx4 v[102:103], off
	v_lshl_add_u64 v[102:103], v[102:103], 0, s[2:3]
	v_mfma_f32_16x16x32_bf16 v[16:19], v[226:229], v[140:143], v[16:19]
	s_add_u32 m0, s101, 0x4000
	ds_read_b128 v[218:221], v154 offset:38912
	global_load_lds_dwordx4 v[104:105], off
	v_lshl_add_u64 v[104:105], v[104:105], 0, s[2:3]
	v_mfma_f32_16x16x32_bf16 v[20:23], v[226:229], v[144:147], v[20:23]
	ds_read_b128 v[186:189], v150 offset:26624
	v_mfma_f32_16x16x32_bf16 v[24:27], v[226:229], v[116:119], v[24:27]
	ds_read_b128 v[190:193], v150 offset:28672
	v_mfma_f32_16x16x32_bf16 v[28:31], v[226:229], v[120:123], v[28:31]
	ds_read_b128 v[194:197], v150 offset:30720
	v_mfma_f32_16x16x32_bf16 v[32:35], v[230:233], v[140:143], v[32:35]
	ds_read_b128 v[198:201], v150 offset:32768
	v_mfma_f32_16x16x32_bf16 v[36:39], v[230:233], v[144:147], v[36:39]
	ds_read_b128 v[202:205], v150 offset:34816
	v_mfma_f32_16x16x32_bf16 v[40:43], v[230:233], v[116:119], v[40:43]
	v_mfma_f32_16x16x32_bf16 v[44:47], v[230:233], v[120:123], v[44:47]
	v_mfma_f32_16x16x32_bf16 v[48:51], v[234:237], v[140:143], v[48:51]
	v_mfma_f32_16x16x32_bf16 v[52:55], v[234:237], v[144:147], v[52:55]
	v_mfma_f32_16x16x32_bf16 v[56:59], v[234:237], v[116:119], v[56:59]
	v_mfma_f32_16x16x32_bf16 v[60:63], v[234:237], v[120:123], v[60:63]
	v_mfma_f32_16x16x32_bf16 v[64:67], v[132:135], v[140:143], v[64:67]
	v_mfma_f32_16x16x32_bf16 v[68:71], v[132:135], v[144:147], v[68:71]
	v_mfma_f32_16x16x32_bf16 v[72:75], v[132:135], v[116:119], v[72:75]
	v_mfma_f32_16x16x32_bf16 v[76:79], v[132:135], v[120:123], v[76:79]
	v_mfma_f32_16x16x32_bf16 v[80:83], v[136:139], v[140:143], v[80:83]
	v_mfma_f32_16x16x32_bf16 v[84:87], v[136:139], v[144:147], v[84:87]
	v_mfma_f32_16x16x32_bf16 v[88:91], v[136:139], v[116:119], v[88:91]
	v_mfma_f32_16x16x32_bf16 v[92:95], v[136:139], v[120:123], v[92:95]
	s_setprio 0
	s_waitcnt lgkmcnt(8)
	v_mfma_f32_16x16x32_bf16 v[0:3], v[182:185], v[206:209], v[0:3]
	s_add_u32 m0, s101, 0x5000
	ds_read_b128 v[222:225], v153 offset:24576
	global_load_lds_dwordx4 v[106:107], off
	v_lshl_add_u64 v[106:107], v[106:107], 0, s[2:3]
	s_waitcnt lgkmcnt(8)
	v_mfma_f32_16x16x32_bf16 v[4:7], v[182:185], v[210:213], v[4:7]
	s_add_u32 m0, s101, 0xc000
	ds_read_b128 v[140:143], v155 offset:32768
	global_load_lds_dwordx4 v[108:109], off
	v_lshl_add_u64 v[108:109], v[108:109], 0, s[2:3]
	s_waitcnt lgkmcnt(8)
	v_mfma_f32_16x16x32_bf16 v[8:11], v[182:185], v[214:217], v[8:11]
	s_add_u32 m0, s101, 0xd000
	ds_read_b128 v[144:147], v155 offset:34816
	global_load_lds_dwordx4 v[110:111], off
	v_lshl_add_u64 v[110:111], v[110:111], 0, s[2:3]
	s_waitcnt lgkmcnt(8)
	v_mfma_f32_16x16x32_bf16 v[12:15], v[182:185], v[218:221], v[12:15]
	s_add_u32 m0, s101, 0xe000
	ds_read_b128 v[116:119], v155 offset:36864
	global_load_lds_dwordx4 v[112:113], off
	v_lshl_add_u64 v[112:113], v[112:113], 0, s[2:3]
	s_waitcnt lgkmcnt(8)
	v_mfma_f32_16x16x32_bf16 v[16:19], v[186:189], v[206:209], v[16:19]
	s_add_u32 m0, s101, 0xf000
	ds_read_b128 v[120:123], v155 offset:38912
	global_load_lds_dwordx4 v[114:115], off
	v_lshl_add_u64 v[114:115], v[114:115], 0, s[2:3]
	v_mfma_f32_16x16x32_bf16 v[20:23], v[186:189], v[210:213], v[20:23]
	ds_read_b128 v[226:229], v153 offset:26624
	v_mfma_f32_16x16x32_bf16 v[24:27], v[186:189], v[214:217], v[24:27]
	ds_read_b128 v[230:233], v153 offset:28672
	v_mfma_f32_16x16x32_bf16 v[28:31], v[186:189], v[218:221], v[28:31]
	ds_read_b128 v[234:237], v153 offset:30720
	s_waitcnt lgkmcnt(11)
	v_mfma_f32_16x16x32_bf16 v[32:35], v[190:193], v[206:209], v[32:35]
	ds_read_b128 v[132:135], v153 offset:32768
	v_mfma_f32_16x16x32_bf16 v[36:39], v[190:193], v[210:213], v[36:39]
	ds_read_b128 v[136:139], v153 offset:34816
	v_mfma_f32_16x16x32_bf16 v[40:43], v[190:193], v[214:217], v[40:43]
	v_mfma_f32_16x16x32_bf16 v[44:47], v[190:193], v[218:221], v[44:47]
	s_waitcnt lgkmcnt(12)
	v_mfma_f32_16x16x32_bf16 v[48:51], v[194:197], v[206:209], v[48:51]
	v_mfma_f32_16x16x32_bf16 v[52:55], v[194:197], v[210:213], v[52:55]
	v_mfma_f32_16x16x32_bf16 v[56:59], v[194:197], v[214:217], v[56:59]
	v_mfma_f32_16x16x32_bf16 v[60:63], v[194:197], v[218:221], v[60:63]
	s_waitcnt lgkmcnt(11)
	v_mfma_f32_16x16x32_bf16 v[64:67], v[198:201], v[206:209], v[64:67]
	v_mfma_f32_16x16x32_bf16 v[68:71], v[198:201], v[210:213], v[68:71]
	v_mfma_f32_16x16x32_bf16 v[72:75], v[198:201], v[214:217], v[72:75]
	v_mfma_f32_16x16x32_bf16 v[76:79], v[198:201], v[218:221], v[76:79]
	s_waitcnt lgkmcnt(10)
	v_mfma_f32_16x16x32_bf16 v[80:83], v[202:205], v[206:209], v[80:83]
	v_mfma_f32_16x16x32_bf16 v[84:87], v[202:205], v[210:213], v[84:87]
	v_mfma_f32_16x16x32_bf16 v[88:91], v[202:205], v[214:217], v[88:91]
	v_mfma_f32_16x16x32_bf16 v[92:95], v[202:205], v[218:221], v[92:95]
	s_waitcnt vmcnt(0) lgkmcnt(0)
	s_barrier
	s_setprio 2
	v_mfma_f32_16x16x32_bf16 v[0:3], v[222:225], v[140:143], v[0:3]
	s_add_u32 m0, s101, 0x6000
	ds_read_b128 v[182:185], v150 offset:0
	global_load_lds_dwordx4 v[96:97], off
	v_lshl_add_u64 v[96:97], v[96:97], 0, s[2:3]
	v_mfma_f32_16x16x32_bf16 v[4:7], v[222:225], v[144:147], v[4:7]
	s_add_u32 m0, s101, 0x7000
	ds_read_b128 v[206:209], v154 offset:16384
	global_load_lds_dwordx4 v[98:99], off
	v_lshl_add_u64 v[98:99], v[98:99], 0, s[2:3]
	v_mfma_f32_16x16x32_bf16 v[8:11], v[222:225], v[116:119], v[8:11]
	s_add_u32 m0, s101, 0x8000
	ds_read_b128 v[210:213], v154 offset:18432
	global_load_lds_dwordx4 v[100:101], off
	v_lshl_add_u64 v[100:101], v[100:101], 0, s[2:3]
	v_mfma_f32_16x16x32_bf16 v[12:15], v[222:225], v[120:123], v[12:15]
	s_add_u32 m0, s101, 0x9000
	ds_read_b128 v[214:217], v154 offset:20480
	global_load_lds_dwordx4 v[102:103], off
	v_lshl_add_u64 v[102:103], v[102:103], 0, s[2:3]
	v_mfma_f32_16x16x32_bf16 v[16:19], v[226:229], v[140:143], v[16:19]
	s_add_u32 m0, s101, 0xa000
	ds_read_b128 v[218:221], v154 offset:22528
	global_load_lds_dwordx4 v[104:105], off
	v_lshl_add_u64 v[104:105], v[104:105], 0, s[2:3]
	v_mfma_f32_16x16x32_bf16 v[20:23], v[226:229], v[144:147], v[20:23]
	ds_read_b128 v[186:189], v150 offset:2048
	v_mfma_f32_16x16x32_bf16 v[24:27], v[226:229], v[116:119], v[24:27]
	ds_read_b128 v[190:193], v150 offset:4096
	v_mfma_f32_16x16x32_bf16 v[28:31], v[226:229], v[120:123], v[28:31]
	ds_read_b128 v[194:197], v150 offset:6144
	v_mfma_f32_16x16x32_bf16 v[32:35], v[230:233], v[140:143], v[32:35]
	ds_read_b128 v[198:201], v150 offset:8192
	v_mfma_f32_16x16x32_bf16 v[36:39], v[230:233], v[144:147], v[36:39]
	ds_read_b128 v[202:205], v150 offset:10240
	v_mfma_f32_16x16x32_bf16 v[40:43], v[230:233], v[116:119], v[40:43]
	v_mfma_f32_16x16x32_bf16 v[44:47], v[230:233], v[120:123], v[44:47]
	v_mfma_f32_16x16x32_bf16 v[48:51], v[234:237], v[140:143], v[48:51]
	v_mfma_f32_16x16x32_bf16 v[52:55], v[234:237], v[144:147], v[52:55]
	v_mfma_f32_16x16x32_bf16 v[56:59], v[234:237], v[116:119], v[56:59]
	v_mfma_f32_16x16x32_bf16 v[60:63], v[234:237], v[120:123], v[60:63]
	v_mfma_f32_16x16x32_bf16 v[64:67], v[132:135], v[140:143], v[64:67]
	v_mfma_f32_16x16x32_bf16 v[68:71], v[132:135], v[144:147], v[68:71]
	v_mfma_f32_16x16x32_bf16 v[72:75], v[132:135], v[116:119], v[72:75]
	v_mfma_f32_16x16x32_bf16 v[76:79], v[132:135], v[120:123], v[76:79]
	v_mfma_f32_16x16x32_bf16 v[80:83], v[136:139], v[140:143], v[80:83]
	v_mfma_f32_16x16x32_bf16 v[84:87], v[136:139], v[144:147], v[84:87]
	v_mfma_f32_16x16x32_bf16 v[88:91], v[136:139], v[116:119], v[88:91]
	v_mfma_f32_16x16x32_bf16 v[92:95], v[136:139], v[120:123], v[92:95]
	s_setprio 0
	s_add_i32 s100, s100, -1
	s_cmp_lg_u32 s100, 0
	s_cbranch_scc1 .Lgu2_loop
	s_waitcnt lgkmcnt(8)
	v_mfma_f32_16x16x32_bf16 v[0:3], v[182:185], v[206:209], v[0:3]
	s_add_u32 m0, s101, 0xb000
	ds_read_b128 v[222:225], v153 offset:0
	global_load_lds_dwordx4 v[106:107], off
	v_lshl_add_u64 v[106:107], v[106:107], 0, s[2:3]
	s_waitcnt lgkmcnt(8)
	v_mfma_f32_16x16x32_bf16 v[4:7], v[182:185], v[210:213], v[4:7]
	s_add_u32 m0, s101, 0x10000
	ds_read_b128 v[140:143], v155 offset:16384
	global_load_lds_dwordx4 v[108:109], off
	v_lshl_add_u64 v[108:109], v[108:109], 0, s[2:3]
	s_waitcnt lgkmcnt(8)
	v_mfma_f32_16x16x32_bf16 v[8:11], v[182:185], v[214:217], v[8:11]
	s_add_u32 m0, s101, 0x11000
	ds_read_b128 v[144:147], v155 offset:18432
	global_load_lds_dwordx4 v[110:111], off
	v_lshl_add_u64 v[110:111], v[110:111], 0, s[2:3]
	s_waitcnt lgkmcnt(8)
	v_mfma_f32_16x16x32_bf16 v[12:15], v[182:185], v[218:221], v[12:15]
	s_add_u32 m0, s101, 0x12000
	ds_read_b128 v[116:119], v155 offset:20480
	global_load_lds_dwordx4 v[112:113], off
	v_lshl_add_u64 v[112:113], v[112:113], 0, s[2:3]
	s_waitcnt lgkmcnt(8)
	v_mfma_f32_16x16x32_bf16 v[16:19], v[186:189], v[206:209], v[16:19]
	s_add_u32 m0, s101, 0x13000
	ds_read_b128 v[120:123], v155 offset:22528
	global_load_lds_dwordx4 v[114:115], off
	v_lshl_add_u64 v[114:115], v[114:115], 0, s[2:3]
	v_mfma_f32_16x16x32_bf16 v[20:23], v[186:189], v[210:213], v[20:23]
	ds_read_b128 v[226:229], v153 offset:2048
	v_mfma_f32_16x16x32_bf16 v[24:27], v[186:189], v[214:217], v[24:27]
	ds_read_b128 v[230:233], v153 offset:4096
	v_mfma_f32_16x16x32_bf16 v[28:31], v[186:189], v[218:221], v[28:31]
	ds_read_b128 v[234:237], v153 offset:6144
	s_waitcnt lgkmcnt(11)
	v_mfma_f32_16x16x32_bf16 v[32:35], v[190:193], v[206:209], v[32:35]
	ds_read_b128 v[132:135], v153 offset:8192
	v_mfma_f32_16x16x32_bf16 v[36:39], v[190:193], v[210:213], v[36:39]
	ds_read_b128 v[136:139], v153 offset:10240
	v_mfma_f32_16x16x32_bf16 v[40:43], v[190:193], v[214:217], v[40:43]
	v_mfma_f32_16x16x32_bf16 v[44:47], v[190:193], v[218:221], v[44:47]
	s_waitcnt lgkmcnt(12)
	v_mfma_f32_16x16x32_bf16 v[48:51], v[194:197], v[206:209], v[48:51]
	v_mfma_f32_16x16x32_bf16 v[52:55], v[194:197], v[210:213], v[52:55]
	v_mfma_f32_16x16x32_bf16 v[56:59], v[194:197], v[214:217], v[56:59]
	v_mfma_f32_16x16x32_bf16 v[60:63], v[194:197], v[218:221], v[60:63]
	s_waitcnt lgkmcnt(11)
	v_mfma_f32_16x16x32_bf16 v[64:67], v[198:201], v[206:209], v[64:67]
	v_mfma_f32_16x16x32_bf16 v[68:71], v[198:201], v[210:213], v[68:71]
	v_mfma_f32_16x16x32_bf16 v[72:75], v[198:201], v[214:217], v[72:75]
	v_mfma_f32_16x16x32_bf16 v[76:79], v[198:201], v[218:221], v[76:79]
	s_waitcnt lgkmcnt(10)
	v_mfma_f32_16x16x32_bf16 v[80:83], v[202:205], v[206:209], v[80:83]
	v_mfma_f32_16x16x32_bf16 v[84:87], v[202:205], v[210:213], v[84:87]
	v_mfma_f32_16x16x32_bf16 v[88:91], v[202:205], v[214:217], v[88:91]
	v_mfma_f32_16x16x32_bf16 v[92:95], v[202:205], v[218:221], v[92:95]
	s_waitcnt vmcnt(0) lgkmcnt(0)
	s_barrier
	v_mfma_f32_16x16x32_bf16 v[0:3], v[222:225], v[140:143], v[0:3]
	ds_read_b128 v[182:185], v150 offset:24576
	v_mfma_f32_16x16x32_bf16 v[4:7], v[222:225], v[144:147], v[4:7]
	ds_read_b128 v[206:209], v154 offset:32768
	v_mfma_f32_16x16x32_bf16 v[8:11], v[222:225], v[116:119], v[8:11]
	ds_read_b128 v[210:213], v154 offset:34816
	v_mfma_f32_16x16x32_bf16 v[12:15], v[222:225], v[120:123], v[12:15]
	ds_read_b128 v[214:217], v154 offset:36864
	v_mfma_f32_16x16x32_bf16 v[16:19], v[226:229], v[140:143], v[16:19]
	ds_read_b128 v[218:221], v154 offset:38912
	v_mfma_f32_16x16x32_bf16 v[20:23], v[226:229], v[144:147], v[20:23]
	ds_read_b128 v[186:189], v150 offset:26624
	v_mfma_f32_16x16x32_bf16 v[24:27], v[226:229], v[116:119], v[24:27]
	ds_read_b128 v[190:193], v150 offset:28672
	v_mfma_f32_16x16x32_bf16 v[28:31], v[226:229], v[120:123], v[28:31]
	ds_read_b128 v[194:197], v150 offset:30720
	v_mfma_f32_16x16x32_bf16 v[32:35], v[230:233], v[140:143], v[32:35]
	ds_read_b128 v[198:201], v150 offset:32768
	v_mfma_f32_16x16x32_bf16 v[36:39], v[230:233], v[144:147], v[36:39]
	ds_read_b128 v[202:205], v150 offset:34816
	v_mfma_f32_16x16x32_bf16 v[40:43], v[230:233], v[116:119], v[40:43]
	v_mfma_f32_16x16x32_bf16 v[44:47], v[230:233], v[120:123], v[44:47]
	v_mfma_f32_16x16x32_bf16 v[48:51], v[234:237], v[140:143], v[48:51]
	v_mfma_f32_16x16x32_bf16 v[52:55], v[234:237], v[144:147], v[52:55]
	v_mfma_f32_16x16x32_bf16 v[56:59], v[234:237], v[116:119], v[56:59]
	v_mfma_f32_16x16x32_bf16 v[60:63], v[234:237], v[120:123], v[60:63]
	v_mfma_f32_16x16x32_bf16 v[64:67], v[132:135], v[140:143], v[64:67]
	v_mfma_f32_16x16x32_bf16 v[68:71], v[132:135], v[144:147], v[68:71]
	v_mfma_f32_16x16x32_bf16 v[72:75], v[132:135], v[116:119], v[72:75]
	v_mfma_f32_16x16x32_bf16 v[76:79], v[132:135], v[120:123], v[76:79]
	v_mfma_f32_16x16x32_bf16 v[80:83], v[136:139], v[140:143], v[80:83]
	v_mfma_f32_16x16x32_bf16 v[84:87], v[136:139], v[144:147], v[84:87]
	v_mfma_f32_16x16x32_bf16 v[88:91], v[136:139], v[116:119], v[88:91]
	v_mfma_f32_16x16x32_bf16 v[92:95], v[136:139], v[120:123], v[92:95]
	s_waitcnt lgkmcnt(8)
	v_mfma_f32_16x16x32_bf16 v[0:3], v[182:185], v[206:209], v[0:3]
	ds_read_b128 v[222:225], v153 offset:24576
	s_waitcnt lgkmcnt(8)
	v_mfma_f32_16x16x32_bf16 v[4:7], v[182:185], v[210:213], v[4:7]
	ds_read_b128 v[140:143], v155 offset:32768
	s_waitcnt lgkmcnt(8)
	v_mfma_f32_16x16x32_bf16 v[8:11], v[182:185], v[214:217], v[8:11]
	ds_read_b128 v[144:147], v155 offset:34816
	s_waitcnt lgkmcnt(8)
	v_mfma_f32_16x16x32_bf16 v[12:15], v[182:185], v[218:221], v[12:15]
	ds_read_b128 v[116:119], v155 offset:36864
	s_waitcnt lgkmcnt(8)
	v_mfma_f32_16x16x32_bf16 v[16:19], v[186:189], v[206:209], v[16:19]
	ds_read_b128 v[120:123], v155 offset:38912
	v_mfma_f32_16x16x32_bf16 v[20:23], v[186:189], v[210:213], v[20:23]
	ds_read_b128 v[226:229], v153 offset:26624
	v_mfma_f32_16x16x32_bf16 v[24:27], v[186:189], v[214:217], v[24:27]
	ds_read_b128 v[230:233], v153 offset:28672
	v_mfma_f32_16x16x32_bf16 v[28:31], v[186:189], v[218:221], v[28:31]
	ds_read_b128 v[234:237], v153 offset:30720
	s_waitcnt lgkmcnt(11)
	v_mfma_f32_16x16x32_bf16 v[32:35], v[190:193], v[206:209], v[32:35]
	ds_read_b128 v[132:135], v153 offset:32768
	v_mfma_f32_16x16x32_bf16 v[36:39], v[190:193], v[210:213], v[36:39]
	ds_read_b128 v[136:139], v153 offset:34816
	v_mfma_f32_16x16x32_bf16 v[40:43], v[190:193], v[214:217], v[40:43]
	v_mfma_f32_16x16x32_bf16 v[44:47], v[190:193], v[218:221], v[44:47]
	s_waitcnt lgkmcnt(12)
	v_mfma_f32_16x16x32_bf16 v[48:51], v[194:197], v[206:209], v[48:51]
	v_mfma_f32_16x16x32_bf16 v[52:55], v[194:197], v[210:213], v[52:55]
	v_mfma_f32_16x16x32_bf16 v[56:59], v[194:197], v[214:217], v[56:59]
	v_mfma_f32_16x16x32_bf16 v[60:63], v[194:197], v[218:221], v[60:63]
	s_waitcnt lgkmcnt(11)
	v_mfma_f32_16x16x32_bf16 v[64:67], v[198:201], v[206:209], v[64:67]
	v_mfma_f32_16x16x32_bf16 v[68:71], v[198:201], v[210:213], v[68:71]
	v_mfma_f32_16x16x32_bf16 v[72:75], v[198:201], v[214:217], v[72:75]
	v_mfma_f32_16x16x32_bf16 v[76:79], v[198:201], v[218:221], v[76:79]
	s_waitcnt lgkmcnt(10)
	v_mfma_f32_16x16x32_bf16 v[80:83], v[202:205], v[206:209], v[80:83]
	v_mfma_f32_16x16x32_bf16 v[84:87], v[202:205], v[210:213], v[84:87]
	v_mfma_f32_16x16x32_bf16 v[88:91], v[202:205], v[214:217], v[88:91]
	v_mfma_f32_16x16x32_bf16 v[92:95], v[202:205], v[218:221], v[92:95]
	s_waitcnt vmcnt(0) lgkmcnt(0)
	s_barrier
	v_mfma_f32_16x16x32_bf16 v[0:3], v[222:225], v[140:143], v[0:3]
	v_mfma_f32_16x16x32_bf16 v[4:7], v[222:225], v[144:147], v[4:7]
	v_mfma_f32_16x16x32_bf16 v[8:11], v[222:225], v[116:119], v[8:11]
	v_mfma_f32_16x16x32_bf16 v[12:15], v[222:225], v[120:123], v[12:15]
	v_mfma_f32_16x16x32_bf16 v[16:19], v[226:229], v[140:143], v[16:19]
	v_mfma_f32_16x16x32_bf16 v[20:23], v[226:229], v[144:147], v[20:23]
	v_mfma_f32_16x16x32_bf16 v[24:27], v[226:229], v[116:119], v[24:27]
	v_mfma_f32_16x16x32_bf16 v[28:31], v[226:229], v[120:123], v[28:31]
	v_mfma_f32_16x16x32_bf16 v[32:35], v[230:233], v[140:143], v[32:35]
	v_mfma_f32_16x16x32_bf16 v[36:39], v[230:233], v[144:147], v[36:39]
	v_mfma_f32_16x16x32_bf16 v[40:43], v[230:233], v[116:119], v[40:43]
	v_mfma_f32_16x16x32_bf16 v[44:47], v[230:233], v[120:123], v[44:47]
	v_mfma_f32_16x16x32_bf16 v[48:51], v[234:237], v[140:143], v[48:51]
	v_mfma_f32_16x16x32_bf16 v[52:55], v[234:237], v[144:147], v[52:55]
	v_mfma_f32_16x16x32_bf16 v[56:59], v[234:237], v[116:119], v[56:59]
	v_mfma_f32_16x16x32_bf16 v[60:63], v[234:237], v[120:123], v[60:63]
	v_mfma_f32_16x16x32_bf16 v[64:67], v[132:135], v[140:143], v[64:67]
	v_mfma_f32_16x16x32_bf16 v[68:71], v[132:135], v[144:147], v[68:71]
	v_mfma_f32_16x16x32_bf16 v[72:75], v[132:135], v[116:119], v[72:75]
	v_mfma_f32_16x16x32_bf16 v[76:79], v[132:135], v[120:123], v[76:79]
	v_mfma_f32_16x16x32_bf16 v[80:83], v[136:139], v[140:143], v[80:83]
	v_mfma_f32_16x16x32_bf16 v[84:87], v[136:139], v[144:147], v[84:87]
	v_mfma_f32_16x16x32_bf16 v[88:91], v[136:139], v[116:119], v[88:91]
	v_mfma_f32_16x16x32_bf16 v[92:95], v[136:139], v[120:123], v[92:95]
	s_nop 7
	s_nop 7
	s_branch .LBB0_82

.Lrs16_loop:
	s_waitcnt lgkmcnt(6)
	v_mfma_f32_16x16x32_bf16 v[0:3], v[88:91], v[112:115], v[0:3]
	s_add_u32 m0, s101, 0xb000
	ds_read_b128 v[182:185], v121 offset:0
	global_load_lds_dwordx4 v[56:57], off
	v_lshl_add_u64 v[56:57], v[56:57], 0, s[2:3]
	s_waitcnt lgkmcnt(6)
	v_mfma_f32_16x16x32_bf16 v[4:7], v[88:91], v[116:119], v[4:7]
	s_add_u32 m0, s101, 0xc000
	ds_read_b128 v[206:209], v123 offset:24576
	global_load_lds_dwordx4 v[58:59], off
	v_lshl_add_u64 v[58:59], v[58:59], 0, s[2:3]
	s_waitcnt lgkmcnt(6)
	v_mfma_f32_16x16x32_bf16 v[8:11], v[92:95], v[112:115], v[8:11]
	s_add_u32 m0, s101, 0xd000
	ds_read_b128 v[210:213], v123 offset:26624
	global_load_lds_dwordx4 v[60:61], off
	v_lshl_add_u64 v[60:61], v[60:61], 0, s[2:3]
	v_mfma_f32_16x16x32_bf16 v[12:15], v[92:95], v[116:119], v[12:15]
	ds_read_b128 v[186:189], v121 offset:2048
	s_waitcnt lgkmcnt(7)
	v_mfma_f32_16x16x32_bf16 v[16:19], v[96:99], v[112:115], v[16:19]
	ds_read_b128 v[190:193], v121 offset:4096
	v_mfma_f32_16x16x32_bf16 v[20:23], v[96:99], v[116:119], v[20:23]
	ds_read_b128 v[194:197], v121 offset:6144
	s_waitcnt lgkmcnt(8)
	v_mfma_f32_16x16x32_bf16 v[24:27], v[100:103], v[112:115], v[24:27]
	ds_read_b128 v[198:201], v121 offset:8192
	v_mfma_f32_16x16x32_bf16 v[28:31], v[100:103], v[116:119], v[28:31]
	ds_read_b128 v[202:205], v121 offset:10240
	s_waitcnt lgkmcnt(9)
	v_mfma_f32_16x16x32_bf16 v[32:35], v[104:107], v[112:115], v[32:35]
	v_mfma_f32_16x16x32_bf16 v[36:39], v[104:107], v[116:119], v[36:39]
	s_waitcnt lgkmcnt(8)
	v_mfma_f32_16x16x32_bf16 v[40:43], v[108:111], v[112:115], v[40:43]
	v_mfma_f32_16x16x32_bf16 v[44:47], v[108:111], v[116:119], v[44:47]
	s_waitcnt vmcnt(0) lgkmcnt(0)
	s_barrier
	s_setprio 2
	v_mfma_f32_16x16x32_bf16 v[0:3], v[182:185], v[206:209], v[0:3]
	s_add_u32 m0, s101, 0x0
	ds_read_b128 v[88:91], v120 offset:12288
	global_load_lds_dwordx4 v[48:49], off
	v_lshl_add_u64 v[48:49], v[48:49], 0, s[2:3]
	v_mfma_f32_16x16x32_bf16 v[4:7], v[182:185], v[210:213], v[4:7]
	s_add_u32 m0, s101, 0x1000
	ds_read_b128 v[112:115], v122 offset:40960
	global_load_lds_dwordx4 v[50:51], off
	v_lshl_add_u64 v[50:51], v[50:51], 0, s[2:3]
	v_mfma_f32_16x16x32_bf16 v[8:11], v[186:189], v[206:209], v[8:11]
	s_add_u32 m0, s101, 0x2000
	ds_read_b128 v[116:119], v122 offset:43008
	global_load_lds_dwordx4 v[52:53], off
	v_lshl_add_u64 v[52:53], v[52:53], 0, s[2:3]
	v_mfma_f32_16x16x32_bf16 v[12:15], v[186:189], v[210:213], v[12:15]
	s_add_u32 m0, s101, 0x6000
	ds_read_b128 v[92:95], v120 offset:14336
	global_load_lds_dwordx4 v[54:55], off
	v_lshl_add_u64 v[54:55], v[54:55], 0, s[2:3]
	v_mfma_f32_16x16x32_bf16 v[16:19], v[190:193], v[206:209], v[16:19]
	ds_read_b128 v[96:99], v120 offset:16384
	v_mfma_f32_16x16x32_bf16 v[20:23], v[190:193], v[210:213], v[20:23]
	ds_read_b128 v[100:103], v120 offset:18432
	v_mfma_f32_16x16x32_bf16 v[24:27], v[194:197], v[206:209], v[24:27]
	ds_read_b128 v[104:107], v120 offset:20480
	v_mfma_f32_16x16x32_bf16 v[28:31], v[194:197], v[210:213], v[28:31]
	ds_read_b128 v[108:111], v120 offset:22528
	v_mfma_f32_16x16x32_bf16 v[32:35], v[198:201], v[206:209], v[32:35]
	v_mfma_f32_16x16x32_bf16 v[36:39], v[198:201], v[210:213], v[36:39]
	v_mfma_f32_16x16x32_bf16 v[40:43], v[202:205], v[206:209], v[40:43]
	v_mfma_f32_16x16x32_bf16 v[44:47], v[202:205], v[210:213], v[44:47]
	s_setprio 0
	s_waitcnt lgkmcnt(6)
	v_mfma_f32_16x16x32_bf16 v[0:3], v[88:91], v[112:115], v[0:3]
	s_add_u32 m0, s101, 0x7000
	ds_read_b128 v[182:185], v121 offset:12288
	global_load_lds_dwordx4 v[56:57], off
	v_lshl_add_u64 v[56:57], v[56:57], 0, s[2:3]
	s_waitcnt lgkmcnt(6)
	v_mfma_f32_16x16x32_bf16 v[4:7], v[88:91], v[116:119], v[4:7]
	s_add_u32 m0, s101, 0x8000
	ds_read_b128 v[206:209], v123 offset:40960
	global_load_lds_dwordx4 v[58:59], off
	v_lshl_add_u64 v[58:59], v[58:59], 0, s[2:3]
	s_waitcnt lgkmcnt(6)
	v_mfma_f32_16x16x32_bf16 v[8:11], v[92:95], v[112:115], v[8:11]
	s_add_u32 m0, s101, 0x9000
	ds_read_b128 v[210:213], v123 offset:43008
	global_load_lds_dwordx4 v[60:61], off
	v_lshl_add_u64 v[60:61], v[60:61], 0, s[2:3]
	v_mfma_f32_16x16x32_bf16 v[12:15], v[92:95], v[116:119], v[12:15]
	ds_read_b128 v[186:189], v121 offset:14336
	s_waitcnt lgkmcnt(7)
	v_mfma_f32_16x16x32_bf16 v[16:19], v[96:99], v[112:115], v[16:19]
	ds_read_b128 v[190:193], v121 offset:16384
	v_mfma_f32_16x16x32_bf16 v[20:23], v[96:99], v[116:119], v[20:23]
	ds_read_b128 v[194:197], v121 offset:18432
	s_waitcnt lgkmcnt(8)
	v_mfma_f32_16x16x32_bf16 v[24:27], v[100:103], v[112:115], v[24:27]
	ds_read_b128 v[198:201], v121 offset:20480
	v_mfma_f32_16x16x32_bf16 v[28:31], v[100:103], v[116:119], v[28:31]
	ds_read_b128 v[202:205], v121 offset:22528
	s_waitcnt lgkmcnt(9)
	v_mfma_f32_16x16x32_bf16 v[32:35], v[104:107], v[112:115], v[32:35]
	v_mfma_f32_16x16x32_bf16 v[36:39], v[104:107], v[116:119], v[36:39]
	s_waitcnt lgkmcnt(8)
	v_mfma_f32_16x16x32_bf16 v[40:43], v[108:111], v[112:115], v[40:43]
	v_mfma_f32_16x16x32_bf16 v[44:47], v[108:111], v[116:119], v[44:47]
	s_waitcnt vmcnt(0) lgkmcnt(0)
	s_barrier
	s_setprio 2
	v_mfma_f32_16x16x32_bf16 v[0:3], v[182:185], v[206:209], v[0:3]
	s_add_u32 m0, s101, 0x3000
	ds_read_b128 v[88:91], v120 offset:0
	global_load_lds_dwordx4 v[48:49], off
	v_lshl_add_u64 v[48:49], v[48:49], 0, s[2:3]
	v_mfma_f32_16x16x32_bf16 v[4:7], v[182:185], v[210:213], v[4:7]
	s_add_u32 m0, s101, 0x4000
	ds_read_b128 v[112:115], v122 offset:24576
	global_load_lds_dwordx4 v[50:51], off
	v_lshl_add_u64 v[50:51], v[50:51], 0, s[2:3]
	v_mfma_f32_16x16x32_bf16 v[8:11], v[186:189], v[206:209], v[8:11]
	s_add_u32 m0, s101, 0x5000
	ds_read_b128 v[116:119], v122 offset:26624
	global_load_lds_dwordx4 v[52:53], off
	v_lshl_add_u64 v[52:53], v[52:53], 0, s[2:3]
	v_mfma_f32_16x16x32_bf16 v[12:15], v[186:189], v[210:213], v[12:15]
	s_add_u32 m0, s101, 0xa000
	ds_read_b128 v[92:95], v120 offset:2048
	global_load_lds_dwordx4 v[54:55], off
	v_lshl_add_u64 v[54:55], v[54:55], 0, s[2:3]
	v_mfma_f32_16x16x32_bf16 v[16:19], v[190:193], v[206:209], v[16:19]
	ds_read_b128 v[96:99], v120 offset:4096
	v_mfma_f32_16x16x32_bf16 v[20:23], v[190:193], v[210:213], v[20:23]
	ds_read_b128 v[100:103], v120 offset:6144
	v_mfma_f32_16x16x32_bf16 v[24:27], v[194:197], v[206:209], v[24:27]
	ds_read_b128 v[104:107], v120 offset:8192
	v_mfma_f32_16x16x32_bf16 v[28:31], v[194:197], v[210:213], v[28:31]
	ds_read_b128 v[108:111], v120 offset:10240
	v_mfma_f32_16x16x32_bf16 v[32:35], v[198:201], v[206:209], v[32:35]
	v_mfma_f32_16x16x32_bf16 v[36:39], v[198:201], v[210:213], v[36:39]
	v_mfma_f32_16x16x32_bf16 v[40:43], v[202:205], v[206:209], v[40:43]
	v_mfma_f32_16x16x32_bf16 v[44:47], v[202:205], v[210:213], v[44:47]
	s_setprio 0
	s_add_i32 s100, s100, -1
	s_cmp_lg_u32 s100, 0
	s_cbranch_scc1 .Lrs16_loop
	s_waitcnt lgkmcnt(6)
	v_mfma_f32_16x16x32_bf16 v[0:3], v[88:91], v[112:115], v[0:3]
	s_add_u32 m0, s101, 0xb000
	ds_read_b128 v[182:185], v121 offset:0
	global_load_lds_dwordx4 v[56:57], off
	v_lshl_add_u64 v[56:57], v[56:57], 0, s[2:3]
	s_waitcnt lgkmcnt(6)
	v_mfma_f32_16x16x32_bf16 v[4:7], v[88:91], v[116:119], v[4:7]
	s_add_u32 m0, s101, 0xc000
	ds_read_b128 v[206:209], v123 offset:24576
	global_load_lds_dwordx4 v[58:59], off
	v_lshl_add_u64 v[58:59], v[58:59], 0, s[2:3]
	s_waitcnt lgkmcnt(6)
	v_mfma_f32_16x16x32_bf16 v[8:11], v[92:95], v[112:115], v[8:11]
	s_add_u32 m0, s101, 0xd000
	ds_read_b128 v[210:213], v123 offset:26624
	global_load_lds_dwordx4 v[60:61], off
	v_lshl_add_u64 v[60:61], v[60:61], 0, s[2:3]
	v_mfma_f32_16x16x32_bf16 v[12:15], v[92:95], v[116:119], v[12:15]
	ds_read_b128 v[186:189], v121 offset:2048
	s_waitcnt lgkmcnt(7)
	v_mfma_f32_16x16x32_bf16 v[16:19], v[96:99], v[112:115], v[16:19]
	ds_read_b128 v[190:193], v121 offset:4096
	v_mfma_f32_16x16x32_bf16 v[20:23], v[96:99], v[116:119], v[20:23]
	ds_read_b128 v[194:197], v121 offset:6144
	s_waitcnt lgkmcnt(8)
	v_mfma_f32_16x16x32_bf16 v[24:27], v[100:103], v[112:115], v[24:27]
	ds_read_b128 v[198:201], v121 offset:8192
	v_mfma_f32_16x16x32_bf16 v[28:31], v[100:103], v[116:119], v[28:31]
	ds_read_b128 v[202:205], v121 offset:10240
	s_waitcnt lgkmcnt(9)
	v_mfma_f32_16x16x32_bf16 v[32:35], v[104:107], v[112:115], v[32:35]
	v_mfma_f32_16x16x32_bf16 v[36:39], v[104:107], v[116:119], v[36:39]
	s_waitcnt lgkmcnt(8)
	v_mfma_f32_16x16x32_bf16 v[40:43], v[108:111], v[112:115], v[40:43]
	v_mfma_f32_16x16x32_bf16 v[44:47], v[108:111], v[116:119], v[44:47]
	s_waitcnt vmcnt(0) lgkmcnt(0)
	s_barrier
	v_mfma_f32_16x16x32_bf16 v[0:3], v[182:185], v[206:209], v[0:3]
	ds_read_b128 v[88:91], v120 offset:12288
	v_mfma_f32_16x16x32_bf16 v[4:7], v[182:185], v[210:213], v[4:7]
	ds_read_b128 v[112:115], v122 offset:40960
	v_mfma_f32_16x16x32_bf16 v[8:11], v[186:189], v[206:209], v[8:11]
	ds_read_b128 v[116:119], v122 offset:43008
	v_mfma_f32_16x16x32_bf16 v[12:15], v[186:189], v[210:213], v[12:15]
	ds_read_b128 v[92:95], v120 offset:14336
	v_mfma_f32_16x16x32_bf16 v[16:19], v[190:193], v[206:209], v[16:19]
	ds_read_b128 v[96:99], v120 offset:16384
	v_mfma_f32_16x16x32_bf16 v[20:23], v[190:193], v[210:213], v[20:23]
	ds_read_b128 v[100:103], v120 offset:18432
	v_mfma_f32_16x16x32_bf16 v[24:27], v[194:197], v[206:209], v[24:27]
	ds_read_b128 v[104:107], v120 offset:20480
	v_mfma_f32_16x16x32_bf16 v[28:31], v[194:197], v[210:213], v[28:31]
	ds_read_b128 v[108:111], v120 offset:22528
	v_mfma_f32_16x16x32_bf16 v[32:35], v[198:201], v[206:209], v[32:35]
	v_mfma_f32_16x16x32_bf16 v[36:39], v[198:201], v[210:213], v[36:39]
	v_mfma_f32_16x16x32_bf16 v[40:43], v[202:205], v[206:209], v[40:43]
	v_mfma_f32_16x16x32_bf16 v[44:47], v[202:205], v[210:213], v[44:47]
	s_waitcnt lgkmcnt(6)
	v_mfma_f32_16x16x32_bf16 v[0:3], v[88:91], v[112:115], v[0:3]
	ds_read_b128 v[182:185], v121 offset:12288
	s_waitcnt lgkmcnt(6)
	v_mfma_f32_16x16x32_bf16 v[4:7], v[88:91], v[116:119], v[4:7]
	ds_read_b128 v[206:209], v123 offset:40960
	s_waitcnt lgkmcnt(6)
	v_mfma_f32_16x16x32_bf16 v[8:11], v[92:95], v[112:115], v[8:11]
	ds_read_b128 v[210:213], v123 offset:43008
	v_mfma_f32_16x16x32_bf16 v[12:15], v[92:95], v[116:119], v[12:15]
	ds_read_b128 v[186:189], v121 offset:14336
	s_waitcnt lgkmcnt(7)
	v_mfma_f32_16x16x32_bf16 v[16:19], v[96:99], v[112:115], v[16:19]
	ds_read_b128 v[190:193], v121 offset:16384
	v_mfma_f32_16x16x32_bf16 v[20:23], v[96:99], v[116:119], v[20:23]
	ds_read_b128 v[194:197], v121 offset:18432
	s_waitcnt lgkmcnt(8)
	v_mfma_f32_16x16x32_bf16 v[24:27], v[100:103], v[112:115], v[24:27]
	ds_read_b128 v[198:201], v121 offset:20480
	v_mfma_f32_16x16x32_bf16 v[28:31], v[100:103], v[116:119], v[28:31]
	ds_read_b128 v[202:205], v121 offset:22528
	s_waitcnt lgkmcnt(9)
	v_mfma_f32_16x16x32_bf16 v[32:35], v[104:107], v[112:115], v[32:35]
	v_mfma_f32_16x16x32_bf16 v[36:39], v[104:107], v[116:119], v[36:39]
	s_waitcnt lgkmcnt(8)
	v_mfma_f32_16x16x32_bf16 v[40:43], v[108:111], v[112:115], v[40:43]
	v_mfma_f32_16x16x32_bf16 v[44:47], v[108:111], v[116:119], v[44:47]
	s_waitcnt vmcnt(0) lgkmcnt(0)
	s_barrier
	v_mfma_f32_16x16x32_bf16 v[0:3], v[182:185], v[206:209], v[0:3]
	v_mfma_f32_16x16x32_bf16 v[4:7], v[182:185], v[210:213], v[4:7]
	v_mfma_f32_16x16x32_bf16 v[8:11], v[186:189], v[206:209], v[8:11]
	v_mfma_f32_16x16x32_bf16 v[12:15], v[186:189], v[210:213], v[12:15]
	v_mfma_f32_16x16x32_bf16 v[16:19], v[190:193], v[206:209], v[16:19]
	v_mfma_f32_16x16x32_bf16 v[20:23], v[190:193], v[210:213], v[20:23]
	v_mfma_f32_16x16x32_bf16 v[24:27], v[194:197], v[206:209], v[24:27]
	v_mfma_f32_16x16x32_bf16 v[28:31], v[194:197], v[210:213], v[28:31]
	v_mfma_f32_16x16x32_bf16 v[32:35], v[198:201], v[206:209], v[32:35]
	v_mfma_f32_16x16x32_bf16 v[36:39], v[198:201], v[210:213], v[36:39]
	v_mfma_f32_16x16x32_bf16 v[40:43], v[202:205], v[206:209], v[40:43]
	v_mfma_f32_16x16x32_bf16 v[44:47], v[202:205], v[210:213], v[44:47]
	s_nop 7
	s_nop 7
	s_branch .Lrs16_epi
